# SSM pass 2: per-group D vector loaded once per item (loop-invariant) instead of every chunk right in front of its first use
# baseline (speedup 1.0000x reference)
; template <bool PASS2>
; __device__ __forceinline__ void ssm_phase(const Params& p, const Frame& F0) {
;     ...
;         bf16x8 uf[4], ufn[4]; u32x2 uw[8], uwn[8];
;         SSM_LOAD_U(uf, uw, 0)
;     ...
;                 const f32x4 dv = *(const f32x4*)(p.in[16] + g * 16 + 4 * gq);
.LBB0_633:
	s_lshl_b32 s24, s0, 14
	s_lshl_b32 s0, s42, 9
	s_add_i32 s16, s0, s24
	v_or_b32_e32 v2, s16, v160
	v_ashrrev_i32_e32 v3, 31, v2
	v_lshlrev_b64 v[52:53], 10, v[2:3]
	v_or_b32_e32 v54, 2, v2
	v_or_b32_e32 v60, 4, v2
	v_or_b32_e32 v2, 6, v2
	s_lshl_b32 s0, s3, 5
	v_ashrrev_i32_e32 v55, 31, v54
	v_ashrrev_i32_e32 v61, 31, v60
	v_ashrrev_i32_e32 v3, 31, v2
	v_lshl_add_u64 v[130:131], v[96:97], 0, s[0:1]
	v_lshlrev_b64 v[54:55], 10, v[54:55]
	v_lshlrev_b64 v[60:61], 10, v[60:61]
	v_lshlrev_b64 v[2:3], 10, v[2:3]
	v_lshl_add_u64 v[52:53], v[130:131], 0, v[52:53]
	v_lshl_add_u64 v[54:55], v[130:131], 0, v[54:55]
	v_lshl_add_u64 v[60:61], v[130:131], 0, v[60:61]
	v_lshl_add_u64 v[2:3], v[130:131], 0, v[2:3]
	global_load_dwordx4 v[56:59], v[52:53], off
	s_nop 0
	global_load_dwordx4 v[52:55], v[54:55], off
	s_nop 0
	global_load_dwordx4 v[64:67], v[60:61], off
	s_nop 0
	global_load_dwordx4 v[60:63], v[2:3], off
	v_or_b32_e32 v2, s16, v159
	v_ashrrev_i32_e32 v3, 31, v2
	v_or_b32_e32 v70, 1, v2
	v_or_b32_e32 v72, 2, v2
	v_or_b32_e32 v74, 3, v2
	v_lshl_add_u64 v[132:133], v[98:99], 0, s[0:1]
	v_lshlrev_b64 v[68:69], 10, v[2:3]
	v_ashrrev_i32_e32 v71, 31, v70
	v_ashrrev_i32_e32 v73, 31, v72
	v_ashrrev_i32_e32 v75, 31, v74
	v_lshl_add_u64 v[68:69], v[132:133], 0, v[68:69]
	v_lshlrev_b64 v[70:71], 10, v[70:71]
	v_lshlrev_b64 v[72:73], 10, v[72:73]
	v_lshlrev_b64 v[74:75], 10, v[74:75]
	v_lshl_add_u64 v[70:71], v[132:133], 0, v[70:71]
	v_lshl_add_u64 v[72:73], v[132:133], 0, v[72:73]
	v_lshl_add_u64 v[74:75], v[132:133], 0, v[74:75]
	global_load_dwordx2 v[156:157], v[68:69], off
	global_load_dwordx2 v[154:155], v[70:71], off
	global_load_dwordx2 v[152:153], v[72:73], off
	global_load_dwordx2 v[150:151], v[74:75], off
	v_or_b32_e32 v68, 4, v2
	v_ashrrev_i32_e32 v69, 31, v68
	v_or_b32_e32 v70, 5, v2
	v_or_b32_e32 v72, 6, v2
	v_or_b32_e32 v2, 7, v2
	v_lshlrev_b64 v[68:69], 10, v[68:69]
	v_ashrrev_i32_e32 v71, 31, v70
	v_ashrrev_i32_e32 v73, 31, v72
	v_ashrrev_i32_e32 v3, 31, v2
	v_lshl_add_u64 v[68:69], v[132:133], 0, v[68:69]
	v_lshlrev_b64 v[70:71], 10, v[70:71]
	v_lshlrev_b64 v[72:73], 10, v[72:73]
	v_lshlrev_b64 v[2:3], 10, v[2:3]
	v_lshl_add_u64 v[70:71], v[132:133], 0, v[70:71]
	v_lshl_add_u64 v[72:73], v[132:133], 0, v[72:73]
	v_lshl_add_u64 v[2:3], v[132:133], 0, v[2:3]
	global_load_dwordx2 v[148:149], v[68:69], off
	global_load_dwordx2 v[146:147], v[70:71], off
	global_load_dwordx2 v[144:145], v[72:73], off
	global_load_dwordx2 v[142:143], v[2:3], off
	s_lshl_b32 s16, s43, 1
	s_add_i32 s16, s16, s87
	s_lshl_b32 s43, s16, 4
	s_lshl_b32 s16, s16, 5
	s_or_b32 s22, s16, s3
	s_ashr_i32 s23, s22, 31
	s_add_i32 s43, s43, 0x8000
	s_lshl_b64 s[16:17], s[22:23], 6
	s_cmp_eq_u32 s42, 31
	v_lshl_add_u64 v[134:135], v[100:101], 0, s[0:1]
	s_cselect_b64 s[18:19], -1, 0
	s_or_b32 s20, s72, s3
	s_lshl_b32 s0, s3, 6
	s_lshl_b32 s3, s90, 7
	s_ashr_i32 s21, s20, 31
	s_lshl_b64 s[22:23], s[22:23], 8
	v_lshl_add_u64 v[140:141], v[110:111], 0, s[0:1]
	global_load_dwordx4 v[228:231], v[140:141], off
	s_add_i32 s0, s82, s24
	s_and_b32 s3, s3, 0x3000
	s_mov_b32 s79, 1
	s_lshl_b64 s[20:21], s[20:21], 6
	v_lshl_add_u64 v[136:137], v[106:107], 0, s[22:23]
	v_lshl_add_u64 v[138:139], v[108:109], 0, s[22:23]
	s_add_i32 s0, s0, s3
	s_mov_b32 s3, 0

; #define SSM_SCAN_STEP(D, SQ) { _Pragma("unroll") for (int r = 0; r < 4; ++r) { \
;                     const float sr = dppf<DPP_SHR(D)>(Er[r]), si = dppf<DPP_SHR(D)>(Ei[r]); \
;                     Er[r] += mr[r] * sr - mi[r] * si; Ei[r] += mr[r] * si + mi[r] * sr; \
;                     if (SQ) { const float nr = mr[r] * mr[r] - mi[r] * mi[r], ni = 2.f * mr[r] * mi[r]; mr[r] = nr; mi[r] = ni; } } }
; template <bool PASS2>
; __device__ __forceinline__ void ssm_phase(const Params& p, const Frame& F0) {
;     ...
;             for (int i = 0; i < 4; ++i) {
;                 __builtin_amdgcn_sched_barrier(0);
;                 f32x4 Er = (f32x4){0.f, 0.f, 0.f, 0.f}, Ei = Er;
; #pragma unroll
;                 for (int ks = 0; ks < 4; ++ks) { Er = __builtin_amdgcn_mfma_f32_16x16x32_bf16(frag[(i * 4 + ks) * 64], uf[ks], Er, 0, 0, 0);
;                                                  Ei = __builtin_amdgcn_mfma_f32_16x16x32_bf16(frag[((i + 4) * 4 + ks) * 64], uf[ks], Ei, 0, 0, 0); }
;                 const f32x4 ma = m1t[8 * i], mb = m1t[8 * i + 1];
;                 float mr[4] = {ma[0], ma[2], mb[0], mb[2]}, mi[4] = {ma[1], ma[3], mb[1], mb[3]};
;                 float hr[4], hi[4];
; #pragma unroll
;                 for (int r = 0; r < 4; ++r) { hr[r] = dppf<DPP_ROR(1)>(xs[i][r]); hi[r] = dppf<DPP_ROR(1)>(xs[i + 4][r]);
;                     if (j == 0) { Er[r] += mr[r] * hr[r] - mi[r] * hi[r]; Ei[r] += mr[r] * hi[r] + mi[r] * hr[r]; } }
;     ...
;                 SSM_SCAN_STEP(1, 1) SSM_SCAN_STEP(2, 1) SSM_SCAN_STEP(4, 1) SSM_SCAN_STEP(8, 0)
.Lssmw_6:
	v_mov_b32_dpp v2, v48 row_ror:1 row_mask:0xf bank_mask:0xf bound_ctrl:1
	s_waitcnt lgkmcnt(3)
	v_mfma_f32_16x16x32_bf16 v[82:85], v[82:85], v[56:59], 0
	v_mov_b32_dpp v91, v46 row_ror:1 row_mask:0xf bank_mask:0xf bound_ctrl:1
	v_mov_b32_dpp v90, v50 row_ror:1 row_mask:0xf bank_mask:0xf bound_ctrl:1
	v_mov_b32_dpp v201, v47 row_ror:1 row_mask:0xf bank_mask:0xf bound_ctrl:1
	s_waitcnt lgkmcnt(1)
	v_mfma_f32_16x16x32_bf16 v[204:207], v[204:207], v[56:59], 0
	v_mov_b32_dpp v200, v51 row_ror:1 row_mask:0xf bank_mask:0xf bound_ctrl:1
	v_mfma_f32_16x16x32_bf16 v[82:85], v[86:89], v[52:55], v[82:85]
	ds_read_b128 v[86:89], v105 offset:14336
	s_waitcnt lgkmcnt(1)
	v_mfma_f32_16x16x32_bf16 v[204:207], v[208:211], v[52:55], v[204:207]
	ds_read_b128 v[208:211], v105 offset:30720
	ds_read_b128 v[212:215], v105 offset:15360
	ds_read_b128 v[216:219], v105 offset:31744
	s_waitcnt lgkmcnt(2)
	v_mfma_f32_16x16x32_bf16 v[204:207], v[208:211], v[64:67], v[204:207]
	v_mfma_f32_16x16x32_bf16 v[82:85], v[86:89], v[64:67], v[82:85]
	ds_read_b128 v[86:89], v198 offset:384
	ds_read_b128 v[220:223], v198 offset:400
	ds_read_b128 v[224:227], v198 offset:1920
	s_waitcnt lgkmcnt(2)
	v_pk_mul_f32 v[78:79], v[86:87], v[2:3] op_sel:[0,1] op_sel_hi:[1,0]
	v_mfma_f32_16x16x32_bf16 v[204:207], v[216:219], v[60:63], v[204:207]
	ds_read_b128 v[216:219], v198 offset:1408
	v_sub_f32_e32 v1, v78, v79
	v_pk_mul_f32 v[78:79], v[86:87], v[2:3]
	v_mov_b32_e32 v208, v86
	v_mfma_f32_16x16x32_bf16 v[82:85], v[212:215], v[60:63], v[82:85]
	v_add_f32_e32 v44, v79, v78
	v_mov_b32_dpp v79, v45 row_ror:1 row_mask:0xf bank_mask:0xf bound_ctrl:1
	v_mov_b32_dpp v78, v49 row_ror:1 row_mask:0xf bank_mask:0xf bound_ctrl:1
	s_nop 0
	v_add_f32_e32 v48, v204, v44
	v_pk_mul_f32 v[44:45], v[88:89], v[78:79] op_sel:[0,1] op_sel_hi:[1,0]
	s_nop 1
	v_add_f32_e32 v1, v82, v1
	v_sub_f32_e32 v44, v44, v45
	v_add_f32_e32 v49, v44, v83
	v_pk_mul_f32 v[44:45], v[88:89], v[78:79]
	v_cndmask_b32_e64 v49, v83, v49, s[10:11]
	v_add_f32_e32 v44, v45, v44
	v_add_f32_e32 v199, v44, v205
	s_waitcnt lgkmcnt(2)
	v_pk_mul_f32 v[44:45], v[220:221], v[90:91] op_sel:[0,1] op_sel_hi:[1,0]
	v_mov_b32_e32 v209, v88
	v_sub_f32_e32 v44, v44, v45
	v_add_f32_e32 v50, v44, v84
	v_pk_mul_f32 v[44:45], v[220:221], v[90:91]
	v_cndmask_b32_e64 v50, v84, v50, s[10:11]
	v_add_f32_e32 v44, v45, v44
	v_add_f32_e32 v46, v44, v206
	v_pk_mul_f32 v[44:45], v[222:223], v[200:201] op_sel:[0,1] op_sel_hi:[1,0]
	v_mov_b32_dpp v83, v49 row_shr:1 row_mask:0xf bank_mask:0xf bound_ctrl:1
	v_sub_f32_e32 v44, v44, v45
	v_add_f32_e32 v51, v44, v85
	v_pk_mul_f32 v[44:45], v[222:223], v[200:201]
	v_cndmask_b32_e64 v51, v85, v51, s[10:11]
	v_add_f32_e32 v44, v45, v44
	v_add_f32_e32 v44, v44, v207
	v_cndmask_b32_e64 v47, v207, v44, s[10:11]
	v_cndmask_b32_e64 v45, v205, v199, s[10:11]
	v_cndmask_b32_e64 v44, v204, v48, s[10:11]
	v_cndmask_b32_e64 v48, v82, v1, s[10:11]
	v_mov_b32_dpp v85, v45 row_shr:1 row_mask:0xf bank_mask:0xf bound_ctrl:1
	v_mov_b32_dpp v84, v44 row_shr:1 row_mask:0xf bank_mask:0xf bound_ctrl:1
	v_mov_b32_dpp v82, v48 row_shr:1 row_mask:0xf bank_mask:0xf bound_ctrl:1
	v_pk_mul_f32 v[210:211], v[208:209], v[84:85]
	v_mov_b32_e32 v212, v87
	v_mov_b32_e32 v213, v89
	ds_read_b128 v[86:89], v198 offset:896
	v_pk_fma_f32 v[210:211], v[212:213], v[82:83], v[210:211]
	v_pk_add_f32 v[44:45], v[210:211], v[44:45]
	v_pk_mul_f32 v[84:85], v[212:213], v[84:85]
	v_pk_fma_f32 v[82:83], v[208:209], v[82:83], v[84:85] neg_lo:[0,0,1] neg_hi:[0,0,1]
	v_mov_b32_dpp v210, v44 row_shr:2 row_mask:0xf bank_mask:0xf bound_ctrl:1
	v_mov_b32_dpp v211, v45 row_shr:2 row_mask:0xf bank_mask:0xf bound_ctrl:1
	v_pk_add_f32 v[48:49], v[82:83], v[48:49]
	s_waitcnt lgkmcnt(0)
	v_pk_mul_f32 v[214:215], v[86:87], v[210:211]
	v_pk_mul_f32 v[84:85], v[88:89], v[210:211]
	v_mov_b32_dpp v82, v48 row_shr:2 row_mask:0xf bank_mask:0xf bound_ctrl:1
	v_mov_b32_dpp v83, v49 row_shr:2 row_mask:0xf bank_mask:0xf bound_ctrl:1
	v_pk_fma_f32 v[84:85], v[86:87], v[82:83], v[84:85] neg_lo:[0,0,1] neg_hi:[0,0,1]
	v_pk_fma_f32 v[82:83], v[88:89], v[82:83], v[214:215]
	ds_read_b64 v[88:89], v198 offset:920
	ds_read_b128 v[212:215], v198 offset:1424
	v_pk_add_f32 v[44:45], v[44:45], v[82:83]
	v_pk_add_f32 v[48:49], v[84:85], v[48:49]
	s_nop 0
	v_mov_b32_dpp v84, v44 row_shr:4 row_mask:0xf bank_mask:0xf bound_ctrl:1
	v_mov_b32_dpp v85, v45 row_shr:4 row_mask:0xf bank_mask:0xf bound_ctrl:1
	v_mov_b32_dpp v82, v48 row_shr:4 row_mask:0xf bank_mask:0xf bound_ctrl:1
	v_mov_b32_dpp v83, v49 row_shr:4 row_mask:0xf bank_mask:0xf bound_ctrl:1
	v_pk_mul_f32 v[86:87], v[218:219], v[84:85]
	v_pk_mul_f32 v[84:85], v[216:217], v[84:85]
	v_pk_fma_f32 v[86:87], v[216:217], v[82:83], v[86:87] neg_lo:[0,0,1] neg_hi:[0,0,1]
	v_pk_fma_f32 v[82:83], v[218:219], v[82:83], v[84:85]
	ds_read_b128 v[216:219], v198 offset:1936
	v_pk_add_f32 v[82:83], v[44:45], v[82:83]
	v_pk_add_f32 v[48:49], v[48:49], v[86:87]
	s_nop 0
	v_mov_b32_dpp v86, v82 row_shr:8 row_mask:0xf bank_mask:0xf bound_ctrl:1
	v_mov_b32_dpp v87, v83 row_shr:8 row_mask:0xf bank_mask:0xf bound_ctrl:1
	v_mov_b32_dpp v84, v48 row_shr:8 row_mask:0xf bank_mask:0xf bound_ctrl:1
	v_mov_b32_dpp v85, v49 row_shr:8 row_mask:0xf bank_mask:0xf bound_ctrl:1
	v_pk_mul_f32 v[44:45], v[226:227], v[86:87]
	v_cndmask_b32_e64 v46, v206, v46, s[10:11]
	v_pk_fma_f32 v[44:45], v[224:225], v[84:85], v[44:45] neg_lo:[0,0,1] neg_hi:[0,0,1]
	v_mov_b32_dpp v207, v47 row_shr:1 row_mask:0xf bank_mask:0xf bound_ctrl:1
	v_pk_add_f32 v[44:45], v[48:49], v[44:45]
	v_pk_mul_f32 v[48:49], v[224:225], v[86:87]
	v_mov_b32_dpp v206, v46 row_shr:1 row_mask:0xf bank_mask:0xf bound_ctrl:1
	v_pk_fma_f32 v[48:49], v[226:227], v[84:85], v[48:49]
	v_mov_b32_dpp v204, v50 row_shr:1 row_mask:0xf bank_mask:0xf bound_ctrl:1
	v_pk_add_f32 v[48:49], v[82:83], v[48:49]
	v_mov_b32_e32 v82, v220
	v_mov_b32_e32 v83, v222
	v_mov_b32_dpp v205, v51 row_shr:1 row_mask:0xf bank_mask:0xf bound_ctrl:1
	v_pk_mul_f32 v[84:85], v[82:83], v[206:207]
	v_mov_b32_e32 v86, v221
	v_mov_b32_e32 v87, v223
	v_pk_fma_f32 v[84:85], v[86:87], v[204:205], v[84:85]
	v_pk_add_f32 v[46:47], v[84:85], v[46:47]
	ds_read_b64 v[84:85], v198 offset:912
	v_pk_mul_f32 v[86:87], v[86:87], v[206:207]
	v_mov_b32_dpp v208, v46 row_shr:2 row_mask:0xf bank_mask:0xf bound_ctrl:1
	v_pk_fma_f32 v[82:83], v[82:83], v[204:205], v[86:87] neg_lo:[0,0,1] neg_hi:[0,0,1]
	v_mov_b32_dpp v209, v47 row_shr:2 row_mask:0xf bank_mask:0xf bound_ctrl:1
	v_pk_add_f32 v[50:51], v[82:83], v[50:51]
	s_waitcnt lgkmcnt(0)
; __device__ __forceinline__ unsigned cvt_pk_bf16(float lo, float hi) { unsigned r; asm("v_cvt_pk_bf16_f32 %0, %1, %2" : "=v"(r) : "v"(lo), "v"(hi)); return r; }
; template <bool PASS2>
; __device__ __forceinline__ void ssm_phase(const Params& p, const Frame& F0) {
;     ...
;                 if constexpr (PASS2) {
;                     float vr[4], vi[4];
; #pragma unroll
;                     for (int r = 0; r < 4; ++r) { const float pr_ = dppf<DPP_ROR(1)>(Er[r]), pi_ = dppf<DPP_ROR(1)>(Ei[r]); vr[r] = (j == 0) ? hr[r] : pr_; vi[r] = (j == 0) ? hi[r] : pi_; }
;                     hw[i >> 1][2 * (i & 1)] = cvt_pk_bf16(vr[0], vr[1]); hw[i >> 1][2 * (i & 1) + 1] = cvt_pk_bf16(vr[2], vr[3]);
;                     hw[2 + (i >> 1)][2 * (i & 1)] = cvt_pk_bf16(vi[0], vi[1]); hw[2 + (i >> 1)][2 * (i & 1) + 1] = cvt_pk_bf16(vi[2], vi[3]);
;                 }
;                 xs[i] = Er; xs[i + 4] = Ei;
;             }
;             __builtin_amdgcn_sched_barrier(0);
;             asm volatile("" ::: "memory");
;             if constexpr (PASS2) {
;                 bf16x8 hf[4];
; #pragma unroll
;                 for (int kap = 0; kap < 4; ++kap) hf[kap] = __builtin_bit_cast(bf16x8, (u32x4){hw[kap][0], hw[kap][1], hw[kap][2], hw[kap][3]});
;                 const f32x4 dv = *(const f32x4*)(p.in[16] + g * 16 + 4 * gq);
; #pragma unroll
;                 for (int t = 0; t < 8; ++t) {
;                     asm volatile("" ::: "memory");
;                     f32x4 y = (f32x4){0.f, 0.f, 0.f, 0.f};
; #pragma unroll
;                     for (int ks = 0; ks < 4; ++ks) y = __builtin_amdgcn_mfma_f32_16x16x32_bf16(frag[(32 + t * 4 + ks) * 64], uf[ks], y, 0, 0, 0);
; #pragma unroll
;                     for (int kap = 0; kap < 4; ++kap) y = __builtin_amdgcn_mfma_f32_16x16x32_bf16(frag[(64 + t * 4 + kap) * 64], hf[kap], y, 0, 0, 0);
;                     if (j < nsub) {
;                         const size_t off = (size_t)(row0 + 8 * j + t) * DSSM + g * 16 + 4 * gq;
;                         const u32x2 uu = uw[t];
;                         const float z0 = gelu_tanh(y[0] + dv[0] * bf_lo(uu.x)), z1 = gelu_tanh(y[1] + dv[1] * bf_hi(uu.x)), z2 = gelu_tanh(y[2] + dv[2] * bf_lo(uu.y)), z3 = gelu_tanh(y[3] + dv[3] * bf_hi(uu.y));
;                         *(u32x2*)(Zb + off) = (u32x2){cvt_pk_bf16(z0, z1), cvt_pk_bf16(z2, z3)};
	v_pk_mul_f32 v[210:211], v[84:85], v[208:209]
	v_mov_b32_dpp v82, v50 row_shr:2 row_mask:0xf bank_mask:0xf bound_ctrl:1
	v_mov_b32_dpp v83, v51 row_shr:2 row_mask:0xf bank_mask:0xf bound_ctrl:1
	v_pk_mul_f32 v[86:87], v[88:89], v[208:209]
	v_pk_fma_f32 v[84:85], v[84:85], v[82:83], v[86:87] neg_lo:[0,0,1] neg_hi:[0,0,1]
	v_pk_fma_f32 v[82:83], v[88:89], v[82:83], v[210:211]
	v_pk_add_f32 v[46:47], v[46:47], v[82:83]
	v_pk_add_f32 v[50:51], v[50:51], v[84:85]
	s_nop 0
	v_mov_b32_dpp v84, v46 row_shr:4 row_mask:0xf bank_mask:0xf bound_ctrl:1
	v_mov_b32_dpp v85, v47 row_shr:4 row_mask:0xf bank_mask:0xf bound_ctrl:1
	v_mov_b32_dpp v82, v50 row_shr:4 row_mask:0xf bank_mask:0xf bound_ctrl:1
	v_mov_b32_dpp v83, v51 row_shr:4 row_mask:0xf bank_mask:0xf bound_ctrl:1
	v_pk_mul_f32 v[86:87], v[214:215], v[84:85]
	v_pk_mul_f32 v[84:85], v[212:213], v[84:85]
	v_pk_fma_f32 v[86:87], v[212:213], v[82:83], v[86:87] neg_lo:[0,0,1] neg_hi:[0,0,1]
	v_pk_fma_f32 v[82:83], v[214:215], v[82:83], v[84:85]
	v_pk_add_f32 v[82:83], v[46:47], v[82:83]
	v_pk_add_f32 v[50:51], v[50:51], v[86:87]
	s_nop 0
	v_mov_b32_dpp v86, v82 row_shr:8 row_mask:0xf bank_mask:0xf bound_ctrl:1
	v_mov_b32_dpp v87, v83 row_shr:8 row_mask:0xf bank_mask:0xf bound_ctrl:1
	v_mov_b32_dpp v84, v50 row_shr:8 row_mask:0xf bank_mask:0xf bound_ctrl:1
	v_mov_b32_dpp v85, v51 row_shr:8 row_mask:0xf bank_mask:0xf bound_ctrl:1
	v_pk_mul_f32 v[46:47], v[218:219], v[86:87]
	v_mov_b32_dpp v1, v44 row_ror:1 row_mask:0xf bank_mask:0xf bound_ctrl:1
	v_pk_fma_f32 v[46:47], v[216:217], v[84:85], v[46:47] neg_lo:[0,0,1] neg_hi:[0,0,1]
	v_cndmask_b32_e64 v1, v1, v3, s[10:11]
	v_pk_add_f32 v[46:47], v[50:51], v[46:47]
	v_pk_mul_f32 v[50:51], v[216:217], v[86:87]
	v_mov_b32_dpp v3, v45 row_ror:1 row_mask:0xf bank_mask:0xf bound_ctrl:1
	v_pk_fma_f32 v[50:51], v[218:219], v[84:85], v[50:51]
	v_cndmask_b32_e64 v3, v3, v79, s[10:11]
	v_pk_add_f32 v[50:51], v[82:83], v[50:51]
	v_mov_b32_dpp v82, v48 row_ror:1 row_mask:0xf bank_mask:0xf bound_ctrl:1
	v_cndmask_b32_e64 v2, v82, v2, s[10:11]
	v_mov_b32_dpp v79, v46 row_ror:1 row_mask:0xf bank_mask:0xf bound_ctrl:1
	v_mov_b32_dpp v82, v49 row_ror:1 row_mask:0xf bank_mask:0xf bound_ctrl:1
	v_cndmask_b32_e64 v78, v82, v78, s[10:11]
	v_mov_b32_dpp v83, v51 row_ror:1 row_mask:0xf bank_mask:0xf bound_ctrl:1
	v_mov_b32_dpp v82, v50 row_ror:1 row_mask:0xf bank_mask:0xf bound_ctrl:1
	v_cndmask_b32_e64 v84, v82, v90, s[10:11]
	v_cndmask_b32_e64 v79, v79, v91, s[10:11]
	v_mov_b32_dpp v82, v47 row_ror:1 row_mask:0xf bank_mask:0xf bound_ctrl:1
	v_cndmask_b32_e64 v85, v82, v201, s[10:11]
	v_cndmask_b32_e64 v86, v83, v200, s[10:11]
	v_cvt_pk_bf16_f32 v82, v1, v3
	v_cvt_pk_bf16_f32 v83, v79, v85
	v_cvt_pk_bf16_f32 v78, v2, v78
	v_cvt_pk_bf16_f32 v79, v84, v86
	ds_read_b128 v[88:91], v105 offset:32768
	ds_read_b128 v[204:207], v105 offset:33792
	ds_read_b128 v[208:211], v105 offset:34816
	v_add_u32_e32 v2, s26, v159
	s_waitcnt lgkmcnt(2)
	v_mfma_f32_16x16x32_bf16 v[88:91], v[88:91], v[56:59], 0
	s_waitcnt lgkmcnt(1)
	v_mfma_f32_16x16x32_bf16 v[88:91], v[204:207], v[52:55], v[88:91]
	ds_read_b128 v[204:207], v105 offset:35840
	s_waitcnt lgkmcnt(1)
	v_mfma_f32_16x16x32_bf16 v[88:91], v[208:211], v[64:67], v[88:91]
	ds_read_b128 v[208:211], v164
	s_waitcnt lgkmcnt(1)
	v_mfma_f32_16x16x32_bf16 v[88:91], v[204:207], v[60:63], v[88:91]
	ds_read_b128 v[204:207], v165
	s_waitcnt lgkmcnt(1)
	v_mfma_f32_16x16x32_bf16 v[88:91], v[208:211], v[72:75], v[88:91]
	ds_read_b128 v[208:211], v166
	s_waitcnt lgkmcnt(1)
	v_mfma_f32_16x16x32_bf16 v[88:91], v[204:207], v[80:83], v[88:91]
	ds_read_b128 v[204:207], v167
	s_waitcnt lgkmcnt(1)
	v_mfma_f32_16x16x32_bf16 v[88:91], v[208:211], v[68:71], v[88:91]
	s_waitcnt lgkmcnt(0)
	v_mfma_f32_16x16x32_bf16 v[88:91], v[204:207], v[76:79], v[88:91]
	s_and_saveexec_b64 s[26:27], s[24:25]
	s_cbranch_execz .LBB0_648
	v_lshlrev_b32_e32 v1, 16, v156
	s_waitcnt vmcnt(0)
	s_nop 3
	v_fma_f32 v1, v228, v1, v88
	v_mul_f32_e32 v3, v1, v1
	v_fmamk_f32 v3, v3, 0xbdd2d3e8, v93
	v_mul_f32_e32 v3, v1, v3
	v_exp_f32_e32 v88, v3
	v_and_b32_e32 v3, 0xffff0000, v156
	v_lshlrev_b32_e32 v199, 16, v157
	v_and_b32_e32 v157, 0xffff0000, v157
	v_fma_f32 v89, v229, v3, v89
	v_fma_f32 v90, v230, v199, v90
	v_fmac_f32_e32 v91, v231, v157
	v_mul_f32_e32 v3, v89, v89
	v_mul_f32_e32 v199, v90, v90
	v_mul_f32_e32 v157, v91, v91
	v_fmamk_f32 v3, v3, 0xbdd2d3e8, v93
	v_fmamk_f32 v199, v199, 0xbdd2d3e8, v93
	v_fmamk_f32 v157, v157, 0xbdd2d3e8, v93
	v_mul_f32_e32 v3, v89, v3
	v_mul_f32_e32 v199, v90, v199
	v_mul_f32_e32 v157, v91, v157
	v_exp_f32_e32 v156, v3
	v_exp_f32_e32 v199, v199
	v_exp_f32_e32 v157, v157
	v_add_f32_e32 v88, 1.0, v88
	v_add_f32_e32 v156, 1.0, v156
	v_add_f32_e32 v199, 1.0, v199
	v_add_f32_e32 v157, 1.0, v157
	v_rcp_f32_e32 v88, v88
	v_rcp_f32_e32 v156, v156
	v_rcp_f32_e32 v199, v199
	v_rcp_f32_e32 v157, v157
	v_ashrrev_i32_e32 v3, 31, v2
	v_mul_f32_e32 v1, v1, v88
	v_mul_f32_e32 v88, v89, v156
	v_mul_f32_e32 v89, v90, v199
	v_mul_f32_e32 v90, v91, v157
	v_cvt_pk_bf16_f32 v89, v89, v90
	v_lshlrev_b64 v[90:91], 10, v[2:3]
	v_lshl_add_u64 v[90:91], v[134:135], 0, v[90:91]
	v_cvt_pk_bf16_f32 v88, v1, v88
	global_store_dwordx2 v[90:91], v[88:89], off
; __device__ __forceinline__ unsigned cvt_pk_bf16(float lo, float hi) { unsigned r; asm("v_cvt_pk_bf16_f32 %0, %1, %2" : "=v"(r) : "v"(lo), "v"(hi)); return r; }
; __device__ __forceinline__ float bf_lo(unsigned w) { return __uint_as_float(w << 16); }
; __device__ __forceinline__ float bf_hi(unsigned w) { return __uint_as_float(w & 0xffff0000u); }
; template <bool PASS2>
; __device__ __forceinline__ void ssm_phase(const Params& p, const Frame& F0) {
;     ...
;                 for (int t = 0; t < 8; ++t) {
;                     asm volatile("" ::: "memory");
;                     f32x4 y = (f32x4){0.f, 0.f, 0.f, 0.f};
; #pragma unroll
;                     for (int ks = 0; ks < 4; ++ks) y = __builtin_amdgcn_mfma_f32_16x16x32_bf16(frag[(32 + t * 4 + ks) * 64], uf[ks], y, 0, 0, 0);
; #pragma unroll
;                     for (int kap = 0; kap < 4; ++kap) y = __builtin_amdgcn_mfma_f32_16x16x32_bf16(frag[(64 + t * 4 + kap) * 64], hf[kap], y, 0, 0, 0);
;                     if (j < nsub) {
;                         const size_t off = (size_t)(row0 + 8 * j + t) * DSSM + g * 16 + 4 * gq;
;                         const u32x2 uu = uw[t];
;                         const float z0 = gelu_tanh(y[0] + dv[0] * bf_lo(uu.x)), z1 = gelu_tanh(y[1] + dv[1] * bf_hi(uu.x)), z2 = gelu_tanh(y[2] + dv[2] * bf_lo(uu.y)), z3 = gelu_tanh(y[3] + dv[3] * bf_hi(uu.y));
;                         *(u32x2*)(Zb + off) = (u32x2){cvt_pk_bf16(z0, z1), cvt_pk_bf16(z2, z3)};
.LBB0_648:
	s_or_b64 exec, exec, s[26:27]
	s_nop 4
	ds_read_b128 v[88:91], v105 offset:36864
	ds_read_b128 v[204:207], v105 offset:37888
	ds_read_b128 v[208:211], v105 offset:38912
	s_waitcnt lgkmcnt(2)
	v_mfma_f32_16x16x32_bf16 v[88:91], v[88:91], v[56:59], 0
	s_waitcnt lgkmcnt(1)
	v_mfma_f32_16x16x32_bf16 v[88:91], v[204:207], v[52:55], v[88:91]
	ds_read_b128 v[204:207], v105 offset:39936
	s_waitcnt lgkmcnt(1)
	v_mfma_f32_16x16x32_bf16 v[88:91], v[208:211], v[64:67], v[88:91]
	ds_read_b128 v[208:211], v168
	s_waitcnt lgkmcnt(1)
	v_mfma_f32_16x16x32_bf16 v[88:91], v[204:207], v[60:63], v[88:91]
	ds_read_b128 v[204:207], v169
	s_waitcnt lgkmcnt(1)
	v_mfma_f32_16x16x32_bf16 v[88:91], v[208:211], v[72:75], v[88:91]
	ds_read_b128 v[208:211], v170
	s_waitcnt lgkmcnt(1)
	v_mfma_f32_16x16x32_bf16 v[88:91], v[204:207], v[80:83], v[88:91]
	ds_read_b128 v[204:207], v171
	s_waitcnt lgkmcnt(1)
	v_mfma_f32_16x16x32_bf16 v[88:91], v[208:211], v[68:71], v[88:91]
	s_waitcnt lgkmcnt(0)
	v_mfma_f32_16x16x32_bf16 v[88:91], v[204:207], v[76:79], v[88:91]
	s_and_saveexec_b64 s[26:27], s[24:25]
	s_cbranch_execz .LBB0_650
	v_lshlrev_b32_e32 v1, 16, v154
	s_waitcnt vmcnt(0)
	s_nop 3
	v_fma_f32 v1, v228, v1, v88
	v_and_b32_e32 v88, 0xffff0000, v154
	v_lshlrev_b32_e32 v154, 16, v155
	v_and_b32_e32 v155, 0xffff0000, v155
	v_fma_f32 v88, v229, v88, v89
	v_fma_f32 v90, v230, v154, v90
	v_fmac_f32_e32 v91, v231, v155
	v_mul_f32_e32 v3, v1, v1
	v_mul_f32_e32 v89, v88, v88
	v_mul_f32_e32 v154, v90, v90
	v_mul_f32_e32 v155, v91, v91
	v_fmamk_f32 v3, v3, 0xbdd2d3e8, v93
	v_fmamk_f32 v89, v89, 0xbdd2d3e8, v93
	v_fmamk_f32 v154, v154, 0xbdd2d3e8, v93
	v_fmamk_f32 v155, v155, 0xbdd2d3e8, v93
	v_mul_f32_e32 v3, v1, v3
	v_mul_f32_e32 v89, v88, v89
	v_mul_f32_e32 v154, v90, v154
	v_mul_f32_e32 v155, v91, v155
	v_exp_f32_e32 v3, v3
	v_exp_f32_e32 v89, v89
	v_exp_f32_e32 v154, v154
	v_exp_f32_e32 v155, v155
	v_add_f32_e32 v3, 1.0, v3
	v_add_f32_e32 v89, 1.0, v89
	v_add_f32_e32 v154, 1.0, v154
	v_add_f32_e32 v155, 1.0, v155
	v_rcp_f32_e32 v3, v3
	v_rcp_f32_e32 v89, v89
	v_rcp_f32_e32 v154, v154
	v_rcp_f32_e32 v155, v155
	v_or_b32_e32 v156, 1, v2
	v_ashrrev_i32_e32 v157, 31, v156
	v_mul_f32_e32 v1, v1, v3
	v_mul_f32_e32 v3, v88, v89
	v_mul_f32_e32 v89, v90, v154
	v_mul_f32_e32 v90, v91, v155
	v_cvt_pk_bf16_f32 v89, v89, v90
	v_lshlrev_b64 v[90:91], 10, v[156:157]
	v_lshl_add_u64 v[90:91], v[134:135], 0, v[90:91]
	v_cvt_pk_bf16_f32 v88, v1, v3
	global_store_dwordx2 v[90:91], v[88:89], off
.LBB0_650:
	s_or_b64 exec, exec, s[26:27]
	s_nop 4
	ds_read_b128 v[88:91], v105 offset:40960
	ds_read_b128 v[154:157], v105 offset:41984
	ds_read_b128 v[204:207], v105 offset:43008
	s_waitcnt lgkmcnt(2)
	v_mfma_f32_16x16x32_bf16 v[88:91], v[88:91], v[56:59], 0
	s_waitcnt lgkmcnt(1)
	v_mfma_f32_16x16x32_bf16 v[88:91], v[154:157], v[52:55], v[88:91]
	ds_read_b128 v[154:157], v105 offset:44032
	s_waitcnt lgkmcnt(1)
	v_mfma_f32_16x16x32_bf16 v[88:91], v[204:207], v[64:67], v[88:91]
	ds_read_b128 v[204:207], v172
	s_waitcnt lgkmcnt(1)
	v_mfma_f32_16x16x32_bf16 v[88:91], v[154:157], v[60:63], v[88:91]
	ds_read_b128 v[154:157], v173
	s_waitcnt lgkmcnt(1)
	v_mfma_f32_16x16x32_bf16 v[88:91], v[204:207], v[72:75], v[88:91]
	ds_read_b128 v[204:207], v174
	s_waitcnt lgkmcnt(1)
	v_mfma_f32_16x16x32_bf16 v[88:91], v[154:157], v[80:83], v[88:91]
	ds_read_b128 v[154:157], v175
	s_waitcnt lgkmcnt(1)
	v_mfma_f32_16x16x32_bf16 v[88:91], v[204:207], v[68:71], v[88:91]
	s_waitcnt lgkmcnt(0)
	v_mfma_f32_16x16x32_bf16 v[88:91], v[154:157], v[76:79], v[88:91]
	s_and_saveexec_b64 s[26:27], s[24:25]
	s_cbranch_execz .LBB0_652
	v_lshlrev_b32_e32 v1, 16, v152
	s_waitcnt vmcnt(0)
	s_nop 3
	v_fma_f32 v1, v228, v1, v88
	v_and_b32_e32 v88, 0xffff0000, v152
	v_lshlrev_b32_e32 v152, 16, v153
	v_and_b32_e32 v153, 0xffff0000, v153
	v_fma_f32 v88, v229, v88, v89
	v_fma_f32 v90, v230, v152, v90
	v_fmac_f32_e32 v91, v231, v153
	v_mul_f32_e32 v3, v1, v1
	v_mul_f32_e32 v89, v88, v88
	v_mul_f32_e32 v152, v90, v90
	v_mul_f32_e32 v153, v91, v91
	v_fmamk_f32 v3, v3, 0xbdd2d3e8, v93
	v_fmamk_f32 v89, v89, 0xbdd2d3e8, v93
	v_fmamk_f32 v152, v152, 0xbdd2d3e8, v93
	v_fmamk_f32 v153, v153, 0xbdd2d3e8, v93
	v_mul_f32_e32 v3, v1, v3
	v_mul_f32_e32 v89, v88, v89
	v_mul_f32_e32 v152, v90, v152
	v_mul_f32_e32 v153, v91, v153
	v_exp_f32_e32 v3, v3
	v_exp_f32_e32 v89, v89
	v_exp_f32_e32 v152, v152
	v_exp_f32_e32 v153, v153
	v_add_f32_e32 v3, 1.0, v3
	v_add_f32_e32 v89, 1.0, v89
	v_add_f32_e32 v152, 1.0, v152
	v_add_f32_e32 v153, 1.0, v153
	v_rcp_f32_e32 v3, v3
	v_rcp_f32_e32 v89, v89
	v_rcp_f32_e32 v152, v152
	v_rcp_f32_e32 v153, v153
	v_or_b32_e32 v154, 2, v2
	v_ashrrev_i32_e32 v155, 31, v154
	v_mul_f32_e32 v1, v1, v3
	v_mul_f32_e32 v3, v88, v89
	v_mul_f32_e32 v89, v90, v152
	v_mul_f32_e32 v90, v91, v153
	v_cvt_pk_bf16_f32 v89, v89, v90
	v_lshlrev_b64 v[90:91], 10, v[154:155]
	v_lshl_add_u64 v[90:91], v[134:135], 0, v[90:91]
	v_cvt_pk_bf16_f32 v88, v1, v3
	global_store_dwordx2 v[90:91], v[88:89], off
; __device__ __forceinline__ unsigned cvt_pk_bf16(float lo, float hi) { unsigned r; asm("v_cvt_pk_bf16_f32 %0, %1, %2" : "=v"(r) : "v"(lo), "v"(hi)); return r; }
; __device__ __forceinline__ float bf_lo(unsigned w) { return __uint_as_float(w << 16); }
; __device__ __forceinline__ float bf_hi(unsigned w) { return __uint_as_float(w & 0xffff0000u); }
; template <bool PASS2>
; __device__ __forceinline__ void ssm_phase(const Params& p, const Frame& F0) {
;     ...
;                 for (int t = 0; t < 8; ++t) {
;                     asm volatile("" ::: "memory");
;                     f32x4 y = (f32x4){0.f, 0.f, 0.f, 0.f};
; #pragma unroll
;                     for (int ks = 0; ks < 4; ++ks) y = __builtin_amdgcn_mfma_f32_16x16x32_bf16(frag[(32 + t * 4 + ks) * 64], uf[ks], y, 0, 0, 0);
; #pragma unroll
;                     for (int kap = 0; kap < 4; ++kap) y = __builtin_amdgcn_mfma_f32_16x16x32_bf16(frag[(64 + t * 4 + kap) * 64], hf[kap], y, 0, 0, 0);
;                     if (j < nsub) {
;                         const size_t off = (size_t)(row0 + 8 * j + t) * DSSM + g * 16 + 4 * gq;
;                         const u32x2 uu = uw[t];
;                         const float z0 = gelu_tanh(y[0] + dv[0] * bf_lo(uu.x)), z1 = gelu_tanh(y[1] + dv[1] * bf_hi(uu.x)), z2 = gelu_tanh(y[2] + dv[2] * bf_lo(uu.y)), z3 = gelu_tanh(y[3] + dv[3] * bf_hi(uu.y));
;                         *(u32x2*)(Zb + off) = (u32x2){cvt_pk_bf16(z0, z1), cvt_pk_bf16(z2, z3)};
.LBB0_652:
	s_or_b64 exec, exec, s[26:27]
	s_nop 4
	ds_read_b128 v[88:91], v105 offset:45056
	ds_read_b128 v[152:155], v105 offset:46080
	ds_read_b128 v[204:207], v105 offset:47104
	s_waitcnt lgkmcnt(2)
	v_mfma_f32_16x16x32_bf16 v[88:91], v[88:91], v[56:59], 0
	s_waitcnt lgkmcnt(1)
	v_mfma_f32_16x16x32_bf16 v[88:91], v[152:155], v[52:55], v[88:91]
	ds_read_b128 v[152:155], v105 offset:48128
	s_waitcnt lgkmcnt(1)
	v_mfma_f32_16x16x32_bf16 v[88:91], v[204:207], v[64:67], v[88:91]
	ds_read_b128 v[204:207], v176
	s_waitcnt lgkmcnt(1)
	v_mfma_f32_16x16x32_bf16 v[88:91], v[152:155], v[60:63], v[88:91]
	ds_read_b128 v[152:155], v177
	s_waitcnt lgkmcnt(1)
	v_mfma_f32_16x16x32_bf16 v[88:91], v[204:207], v[72:75], v[88:91]
	ds_read_b128 v[204:207], v178
	s_waitcnt lgkmcnt(1)
	v_mfma_f32_16x16x32_bf16 v[88:91], v[152:155], v[80:83], v[88:91]
	ds_read_b128 v[152:155], v179
	s_waitcnt lgkmcnt(1)
	v_mfma_f32_16x16x32_bf16 v[88:91], v[204:207], v[68:71], v[88:91]
	s_waitcnt lgkmcnt(0)
	v_mfma_f32_16x16x32_bf16 v[88:91], v[152:155], v[76:79], v[88:91]
	s_and_saveexec_b64 s[26:27], s[24:25]
	s_cbranch_execz .LBB0_654
	v_lshlrev_b32_e32 v1, 16, v150
	s_waitcnt vmcnt(0)
	s_nop 3
	v_fma_f32 v1, v228, v1, v88
	v_and_b32_e32 v88, 0xffff0000, v150
	v_lshlrev_b32_e32 v150, 16, v151
	v_and_b32_e32 v151, 0xffff0000, v151
	v_fma_f32 v88, v229, v88, v89
	v_fma_f32 v90, v230, v150, v90
	v_fmac_f32_e32 v91, v231, v151
	v_mul_f32_e32 v3, v1, v1
	v_mul_f32_e32 v89, v88, v88
	v_mul_f32_e32 v150, v90, v90
	v_mul_f32_e32 v151, v91, v91
	v_fmamk_f32 v3, v3, 0xbdd2d3e8, v93
	v_fmamk_f32 v89, v89, 0xbdd2d3e8, v93
	v_fmamk_f32 v150, v150, 0xbdd2d3e8, v93
	v_fmamk_f32 v151, v151, 0xbdd2d3e8, v93
	v_mul_f32_e32 v3, v1, v3
	v_mul_f32_e32 v89, v88, v89
	v_mul_f32_e32 v150, v90, v150
	v_mul_f32_e32 v151, v91, v151
	v_exp_f32_e32 v3, v3
	v_exp_f32_e32 v89, v89
	v_exp_f32_e32 v150, v150
	v_exp_f32_e32 v151, v151
	v_add_f32_e32 v3, 1.0, v3
	v_add_f32_e32 v89, 1.0, v89
	v_add_f32_e32 v150, 1.0, v150
	v_add_f32_e32 v151, 1.0, v151
	v_rcp_f32_e32 v3, v3
	v_rcp_f32_e32 v89, v89
	v_rcp_f32_e32 v150, v150
	v_rcp_f32_e32 v151, v151
	v_or_b32_e32 v152, 3, v2
	v_ashrrev_i32_e32 v153, 31, v152
	v_mul_f32_e32 v1, v1, v3
	v_mul_f32_e32 v3, v88, v89
	v_mul_f32_e32 v89, v90, v150
	v_mul_f32_e32 v90, v91, v151
	v_cvt_pk_bf16_f32 v89, v89, v90
	v_lshlrev_b64 v[90:91], 10, v[152:153]
	v_lshl_add_u64 v[90:91], v[134:135], 0, v[90:91]
	v_cvt_pk_bf16_f32 v88, v1, v3
	global_store_dwordx2 v[90:91], v[88:89], off
.LBB0_654:
	s_or_b64 exec, exec, s[26:27]
	s_nop 4
	ds_read_b128 v[88:91], v105 offset:49152
	ds_read_b128 v[150:153], v105 offset:50176
	ds_read_b128 v[154:157], v105 offset:51200
	s_waitcnt lgkmcnt(2)
	v_mfma_f32_16x16x32_bf16 v[88:91], v[88:91], v[56:59], 0
	s_waitcnt lgkmcnt(1)
	v_mfma_f32_16x16x32_bf16 v[88:91], v[150:153], v[52:55], v[88:91]
	ds_read_b128 v[150:153], v105 offset:52224
	s_waitcnt lgkmcnt(1)
	v_mfma_f32_16x16x32_bf16 v[88:91], v[154:157], v[64:67], v[88:91]
	ds_read_b128 v[154:157], v180
	s_waitcnt lgkmcnt(1)
	v_mfma_f32_16x16x32_bf16 v[88:91], v[150:153], v[60:63], v[88:91]
	ds_read_b128 v[150:153], v181
	s_waitcnt lgkmcnt(1)
	v_mfma_f32_16x16x32_bf16 v[88:91], v[154:157], v[72:75], v[88:91]
	ds_read_b128 v[154:157], v182
	s_waitcnt lgkmcnt(1)
	v_mfma_f32_16x16x32_bf16 v[88:91], v[150:153], v[80:83], v[88:91]
	ds_read_b128 v[150:153], v183
	s_waitcnt lgkmcnt(1)
	v_mfma_f32_16x16x32_bf16 v[88:91], v[154:157], v[68:71], v[88:91]
	s_waitcnt lgkmcnt(0)
	v_mfma_f32_16x16x32_bf16 v[88:91], v[150:153], v[76:79], v[88:91]
	s_and_saveexec_b64 s[26:27], s[24:25]
	s_cbranch_execz .LBB0_656
	v_lshlrev_b32_e32 v1, 16, v148
	s_waitcnt vmcnt(0)
	s_nop 3
	v_fma_f32 v1, v228, v1, v88
	v_and_b32_e32 v88, 0xffff0000, v148
	v_lshlrev_b32_e32 v148, 16, v149
	v_and_b32_e32 v149, 0xffff0000, v149
	v_fma_f32 v88, v229, v88, v89
	v_fma_f32 v90, v230, v148, v90
	v_fmac_f32_e32 v91, v231, v149
	v_mul_f32_e32 v3, v1, v1
	v_mul_f32_e32 v89, v88, v88
	v_mul_f32_e32 v148, v90, v90
	v_mul_f32_e32 v149, v91, v91
	v_fmamk_f32 v3, v3, 0xbdd2d3e8, v93
	v_fmamk_f32 v89, v89, 0xbdd2d3e8, v93
	v_fmamk_f32 v148, v148, 0xbdd2d3e8, v93
	v_fmamk_f32 v149, v149, 0xbdd2d3e8, v93
	v_mul_f32_e32 v3, v1, v3
	v_mul_f32_e32 v89, v88, v89
	v_mul_f32_e32 v148, v90, v148
	v_mul_f32_e32 v149, v91, v149
	v_exp_f32_e32 v3, v3
	v_exp_f32_e32 v89, v89
	v_exp_f32_e32 v148, v148
	v_exp_f32_e32 v149, v149
	v_add_f32_e32 v3, 1.0, v3
	v_add_f32_e32 v89, 1.0, v89
	v_add_f32_e32 v148, 1.0, v148
	v_add_f32_e32 v149, 1.0, v149
	v_rcp_f32_e32 v3, v3
	v_rcp_f32_e32 v89, v89
	v_rcp_f32_e32 v148, v148
	v_rcp_f32_e32 v149, v149
	v_or_b32_e32 v150, 4, v2
	v_ashrrev_i32_e32 v151, 31, v150
	v_mul_f32_e32 v1, v1, v3
	v_mul_f32_e32 v3, v88, v89
	v_mul_f32_e32 v89, v90, v148
	v_mul_f32_e32 v90, v91, v149
	v_cvt_pk_bf16_f32 v89, v89, v90
	v_lshlrev_b64 v[90:91], 10, v[150:151]
	v_lshl_add_u64 v[90:91], v[134:135], 0, v[90:91]
	v_cvt_pk_bf16_f32 v88, v1, v3
	global_store_dwordx2 v[90:91], v[88:89], off
; __device__ __forceinline__ unsigned cvt_pk_bf16(float lo, float hi) { unsigned r; asm("v_cvt_pk_bf16_f32 %0, %1, %2" : "=v"(r) : "v"(lo), "v"(hi)); return r; }
; __device__ __forceinline__ float bf_lo(unsigned w) { return __uint_as_float(w << 16); }
; __device__ __forceinline__ float bf_hi(unsigned w) { return __uint_as_float(w & 0xffff0000u); }
; template <bool PASS2>
; __device__ __forceinline__ void ssm_phase(const Params& p, const Frame& F0) {
;     ...
;                 for (int t = 0; t < 8; ++t) {
;                     asm volatile("" ::: "memory");
;                     f32x4 y = (f32x4){0.f, 0.f, 0.f, 0.f};
; #pragma unroll
;                     for (int ks = 0; ks < 4; ++ks) y = __builtin_amdgcn_mfma_f32_16x16x32_bf16(frag[(32 + t * 4 + ks) * 64], uf[ks], y, 0, 0, 0);
; #pragma unroll
;                     for (int kap = 0; kap < 4; ++kap) y = __builtin_amdgcn_mfma_f32_16x16x32_bf16(frag[(64 + t * 4 + kap) * 64], hf[kap], y, 0, 0, 0);
;                     if (j < nsub) {
;                         const size_t off = (size_t)(row0 + 8 * j + t) * DSSM + g * 16 + 4 * gq;
;                         const u32x2 uu = uw[t];
;                         const float z0 = gelu_tanh(y[0] + dv[0] * bf_lo(uu.x)), z1 = gelu_tanh(y[1] + dv[1] * bf_hi(uu.x)), z2 = gelu_tanh(y[2] + dv[2] * bf_lo(uu.y)), z3 = gelu_tanh(y[3] + dv[3] * bf_hi(uu.y));
;                         *(u32x2*)(Zb + off) = (u32x2){cvt_pk_bf16(z0, z1), cvt_pk_bf16(z2, z3)};
.LBB0_656:
	s_or_b64 exec, exec, s[26:27]
	s_nop 4
	ds_read_b128 v[88:91], v105 offset:53248
	ds_read_b128 v[148:151], v105 offset:54272
	ds_read_b128 v[152:155], v105 offset:55296
	s_waitcnt lgkmcnt(2)
	v_mfma_f32_16x16x32_bf16 v[88:91], v[88:91], v[56:59], 0
	s_waitcnt lgkmcnt(1)
	v_mfma_f32_16x16x32_bf16 v[88:91], v[148:151], v[52:55], v[88:91]
	ds_read_b128 v[148:151], v105 offset:56320
	s_waitcnt lgkmcnt(1)
	v_mfma_f32_16x16x32_bf16 v[88:91], v[152:155], v[64:67], v[88:91]
	ds_read_b128 v[152:155], v184
	s_waitcnt lgkmcnt(1)
	v_mfma_f32_16x16x32_bf16 v[88:91], v[148:151], v[60:63], v[88:91]
	ds_read_b128 v[148:151], v185
	s_waitcnt lgkmcnt(1)
	v_mfma_f32_16x16x32_bf16 v[88:91], v[152:155], v[72:75], v[88:91]
	ds_read_b128 v[152:155], v186
	s_waitcnt lgkmcnt(1)
	v_mfma_f32_16x16x32_bf16 v[88:91], v[148:151], v[80:83], v[88:91]
	ds_read_b128 v[148:151], v187
	s_waitcnt lgkmcnt(1)
	v_mfma_f32_16x16x32_bf16 v[88:91], v[152:155], v[68:71], v[88:91]
	s_waitcnt lgkmcnt(0)
	v_mfma_f32_16x16x32_bf16 v[88:91], v[148:151], v[76:79], v[88:91]
	s_and_saveexec_b64 s[26:27], s[24:25]
	s_cbranch_execz .LBB0_658
	v_lshlrev_b32_e32 v1, 16, v146
	s_waitcnt vmcnt(0)
	s_nop 3
	v_fma_f32 v1, v228, v1, v88
	v_and_b32_e32 v88, 0xffff0000, v146
	v_lshlrev_b32_e32 v146, 16, v147
	v_and_b32_e32 v147, 0xffff0000, v147
	v_fma_f32 v88, v229, v88, v89
	v_fma_f32 v90, v230, v146, v90
	v_fmac_f32_e32 v91, v231, v147
	v_mul_f32_e32 v3, v1, v1
	v_mul_f32_e32 v89, v88, v88
	v_mul_f32_e32 v146, v90, v90
	v_mul_f32_e32 v147, v91, v91
	v_fmamk_f32 v3, v3, 0xbdd2d3e8, v93
	v_fmamk_f32 v89, v89, 0xbdd2d3e8, v93
	v_fmamk_f32 v146, v146, 0xbdd2d3e8, v93
	v_fmamk_f32 v147, v147, 0xbdd2d3e8, v93
	v_mul_f32_e32 v3, v1, v3
	v_mul_f32_e32 v89, v88, v89
	v_mul_f32_e32 v146, v90, v146
	v_mul_f32_e32 v147, v91, v147
	v_exp_f32_e32 v3, v3
	v_exp_f32_e32 v89, v89
	v_exp_f32_e32 v146, v146
	v_exp_f32_e32 v147, v147
	v_add_f32_e32 v3, 1.0, v3
	v_add_f32_e32 v89, 1.0, v89
	v_add_f32_e32 v146, 1.0, v146
	v_add_f32_e32 v147, 1.0, v147
	v_rcp_f32_e32 v3, v3
	v_rcp_f32_e32 v89, v89
	v_rcp_f32_e32 v146, v146
	v_rcp_f32_e32 v147, v147
	v_or_b32_e32 v148, 5, v2
	v_ashrrev_i32_e32 v149, 31, v148
	v_mul_f32_e32 v1, v1, v3
	v_mul_f32_e32 v3, v88, v89
	v_mul_f32_e32 v89, v90, v146
	v_mul_f32_e32 v90, v91, v147
	v_cvt_pk_bf16_f32 v89, v89, v90
	v_lshlrev_b64 v[90:91], 10, v[148:149]
	v_lshl_add_u64 v[90:91], v[134:135], 0, v[90:91]
	v_cvt_pk_bf16_f32 v88, v1, v3
	global_store_dwordx2 v[90:91], v[88:89], off
; __device__ __forceinline__ unsigned cvt_pk_bf16(float lo, float hi) { unsigned r; asm("v_cvt_pk_bf16_f32 %0, %1, %2" : "=v"(r) : "v"(lo), "v"(hi)); return r; }
; __device__ __forceinline__ float bf_lo(unsigned w) { return __uint_as_float(w << 16); }
; __device__ __forceinline__ float bf_hi(unsigned w) { return __uint_as_float(w & 0xffff0000u); }
; template <bool PASS2>
; __device__ __forceinline__ void ssm_phase(const Params& p, const Frame& F0) {
;     ...
;                 for (int t = 0; t < 8; ++t) {
;                     asm volatile("" ::: "memory");
;                     f32x4 y = (f32x4){0.f, 0.f, 0.f, 0.f};
; #pragma unroll
;                     for (int ks = 0; ks < 4; ++ks) y = __builtin_amdgcn_mfma_f32_16x16x32_bf16(frag[(32 + t * 4 + ks) * 64], uf[ks], y, 0, 0, 0);
; #pragma unroll
;                     for (int kap = 0; kap < 4; ++kap) y = __builtin_amdgcn_mfma_f32_16x16x32_bf16(frag[(64 + t * 4 + kap) * 64], hf[kap], y, 0, 0, 0);
;                     if (j < nsub) {
;                         const size_t off = (size_t)(row0 + 8 * j + t) * DSSM + g * 16 + 4 * gq;
;                         const u32x2 uu = uw[t];
;                         const float z0 = gelu_tanh(y[0] + dv[0] * bf_lo(uu.x)), z1 = gelu_tanh(y[1] + dv[1] * bf_hi(uu.x)), z2 = gelu_tanh(y[2] + dv[2] * bf_lo(uu.y)), z3 = gelu_tanh(y[3] + dv[3] * bf_hi(uu.y));
;                         *(u32x2*)(Zb + off) = (u32x2){cvt_pk_bf16(z0, z1), cvt_pk_bf16(z2, z3)};
.LBB0_658:
	s_or_b64 exec, exec, s[26:27]
	s_nop 4
	ds_read_b128 v[88:91], v105 offset:57344
	ds_read_b128 v[146:149], v105 offset:58368
	ds_read_b128 v[150:153], v105 offset:59392
	s_waitcnt lgkmcnt(2)
	v_mfma_f32_16x16x32_bf16 v[88:91], v[88:91], v[56:59], 0
	s_waitcnt lgkmcnt(1)
	v_mfma_f32_16x16x32_bf16 v[88:91], v[146:149], v[52:55], v[88:91]
	ds_read_b128 v[146:149], v105 offset:60416
	s_waitcnt lgkmcnt(1)
	v_mfma_f32_16x16x32_bf16 v[88:91], v[150:153], v[64:67], v[88:91]
	ds_read_b128 v[150:153], v188
	s_waitcnt lgkmcnt(1)
	v_mfma_f32_16x16x32_bf16 v[88:91], v[146:149], v[60:63], v[88:91]
	ds_read_b128 v[146:149], v189
	s_waitcnt lgkmcnt(1)
	v_mfma_f32_16x16x32_bf16 v[88:91], v[150:153], v[72:75], v[88:91]
	ds_read_b128 v[150:153], v190
	s_waitcnt lgkmcnt(1)
	v_mfma_f32_16x16x32_bf16 v[88:91], v[146:149], v[80:83], v[88:91]
	ds_read_b128 v[146:149], v191
	s_waitcnt lgkmcnt(1)
	v_mfma_f32_16x16x32_bf16 v[88:91], v[150:153], v[68:71], v[88:91]
	s_waitcnt lgkmcnt(0)
	v_mfma_f32_16x16x32_bf16 v[88:91], v[146:149], v[76:79], v[88:91]
	s_and_saveexec_b64 s[26:27], s[24:25]
	s_cbranch_execz .LBB0_660
	v_lshlrev_b32_e32 v1, 16, v144
	s_waitcnt vmcnt(0)
	s_nop 3
	v_fma_f32 v1, v228, v1, v88
	v_and_b32_e32 v88, 0xffff0000, v144
	v_lshlrev_b32_e32 v144, 16, v145
	v_and_b32_e32 v145, 0xffff0000, v145
	v_fma_f32 v88, v229, v88, v89
	v_fma_f32 v90, v230, v144, v90
	v_fmac_f32_e32 v91, v231, v145
	v_mul_f32_e32 v3, v1, v1
	v_mul_f32_e32 v89, v88, v88
	v_mul_f32_e32 v144, v90, v90
	v_mul_f32_e32 v145, v91, v91
	v_fmamk_f32 v3, v3, 0xbdd2d3e8, v93
	v_fmamk_f32 v89, v89, 0xbdd2d3e8, v93
	v_fmamk_f32 v144, v144, 0xbdd2d3e8, v93
	v_fmamk_f32 v145, v145, 0xbdd2d3e8, v93
	v_mul_f32_e32 v3, v1, v3
	v_mul_f32_e32 v89, v88, v89
	v_mul_f32_e32 v144, v90, v144
	v_mul_f32_e32 v145, v91, v145
	v_exp_f32_e32 v3, v3
	v_exp_f32_e32 v89, v89
	v_exp_f32_e32 v144, v144
	v_exp_f32_e32 v145, v145
	v_add_f32_e32 v3, 1.0, v3
	v_add_f32_e32 v89, 1.0, v89
	v_add_f32_e32 v144, 1.0, v144
	v_add_f32_e32 v145, 1.0, v145
	v_rcp_f32_e32 v3, v3
	v_rcp_f32_e32 v89, v89
	v_rcp_f32_e32 v144, v144
	v_rcp_f32_e32 v145, v145
	v_or_b32_e32 v146, 6, v2
	v_ashrrev_i32_e32 v147, 31, v146
	v_mul_f32_e32 v1, v1, v3
	v_mul_f32_e32 v3, v88, v89
	v_mul_f32_e32 v89, v90, v144
	v_mul_f32_e32 v90, v91, v145
	v_cvt_pk_bf16_f32 v89, v89, v90
	v_lshlrev_b64 v[90:91], 10, v[146:147]
	v_lshl_add_u64 v[90:91], v[134:135], 0, v[90:91]
	v_cvt_pk_bf16_f32 v88, v1, v3
	global_store_dwordx2 v[90:91], v[88:89], off
.LBB0_660:
	s_or_b64 exec, exec, s[26:27]
	s_nop 4
	ds_read_b128 v[88:91], v105 offset:61440
	ds_read_b128 v[144:147], v105 offset:62464
	s_waitcnt lgkmcnt(1)
	v_mfma_f32_16x16x32_bf16 v[56:59], v[88:91], v[56:59], 0
	ds_read_b128 v[88:91], v105 offset:63488
	s_waitcnt lgkmcnt(1)
	v_mfma_f32_16x16x32_bf16 v[52:55], v[144:147], v[52:55], v[56:59]
	s_nop 4
	ds_read_b128 v[56:59], v105 offset:64512
	s_waitcnt lgkmcnt(1)
	v_mfma_f32_16x16x32_bf16 v[52:55], v[88:91], v[64:67], v[52:55]
	ds_read_b128 v[64:67], v192
	s_waitcnt lgkmcnt(1)
	v_mfma_f32_16x16x32_bf16 v[52:55], v[56:59], v[60:63], v[52:55]
	ds_read_b128 v[56:59], v193
	ds_read_b128 v[60:63], v194
	s_waitcnt lgkmcnt(2)
	v_mfma_f32_16x16x32_bf16 v[52:55], v[64:67], v[72:75], v[52:55]
	s_waitcnt lgkmcnt(1)
	v_mfma_f32_16x16x32_bf16 v[52:55], v[56:59], v[80:83], v[52:55]
	ds_read_b128 v[56:59], v195
	s_waitcnt lgkmcnt(1)
	v_mfma_f32_16x16x32_bf16 v[52:55], v[60:63], v[68:71], v[52:55]
	s_waitcnt lgkmcnt(0)
	v_mfma_f32_16x16x32_bf16 v[52:55], v[56:59], v[76:79], v[52:55]
	s_and_saveexec_b64 s[26:27], s[24:25]
	s_cbranch_execz .LBB0_662
	v_lshlrev_b32_e32 v1, 16, v142
	s_waitcnt vmcnt(0)
	s_nop 3
	v_fma_f32 v1, v228, v1, v52
	v_mul_f32_e32 v3, v1, v1
	v_fmamk_f32 v3, v3, 0xbdd2d3e8, v93
	v_mul_f32_e32 v3, v1, v3
	v_exp_f32_e32 v52, v3
	v_and_b32_e32 v3, 0xffff0000, v142
	v_lshlrev_b32_e32 v57, 16, v143
	v_fma_f32 v53, v229, v3, v53
	v_fma_f32 v54, v230, v57, v54
	v_and_b32_e32 v58, 0xffff0000, v143
	v_mul_f32_e32 v3, v53, v53
	v_mul_f32_e32 v57, v54, v54
	v_fmac_f32_e32 v55, v231, v58
	v_fmamk_f32 v3, v3, 0xbdd2d3e8, v93
	v_fmamk_f32 v57, v57, 0xbdd2d3e8, v93
	v_mul_f32_e32 v58, v55, v55
	v_mul_f32_e32 v3, v53, v3
	v_mul_f32_e32 v57, v54, v57
	v_fmamk_f32 v58, v58, 0xbdd2d3e8, v93
	v_exp_f32_e32 v56, v3
	v_exp_f32_e32 v57, v57
	v_mul_f32_e32 v58, v55, v58
	v_exp_f32_e32 v58, v58
	v_add_f32_e32 v52, 1.0, v52
	v_add_f32_e32 v56, 1.0, v56
	v_add_f32_e32 v57, 1.0, v57
	v_rcp_f32_e32 v52, v52
	v_rcp_f32_e32 v56, v56
	v_rcp_f32_e32 v57, v57
	v_add_f32_e32 v58, 1.0, v58
	v_or_b32_e32 v2, 7, v2
	v_rcp_f32_e32 v58, v58
	v_ashrrev_i32_e32 v3, 31, v2
	v_lshlrev_b64 v[2:3], 10, v[2:3]
	v_mul_f32_e32 v1, v1, v52
	v_mul_f32_e32 v52, v53, v56
	v_mul_f32_e32 v53, v54, v57
	v_lshl_add_u64 v[2:3], v[134:135], 0, v[2:3]
	v_mul_f32_e32 v54, v55, v58
	v_cvt_pk_bf16_f32 v52, v1, v52
	v_cvt_pk_bf16_f32 v53, v53, v54
	global_store_dwordx2 v[2:3], v[52:53], off
